# FFN1-out K-loop: activation (A) LDS-DMA pieces issued first within each 6-piece staging segment
# speedup vs baseline: 1.0092x; 1.0004x over previous
; #define PG8_STAGE(bufoff, gbase, voff) do { _Pragma("unroll") for (int _i = 0; _i < 2; ++_i) \
;         __builtin_amdgcn_global_load_lds((const unsigned*)((const char*)(gbase) + (voff)[_i]), (PG8_LAS unsigned*)(lds + (bufoff) + ldsw + _i * 8192), 16, 0, 0); } while (0)
; #define PG8_LDA(dst, b, h) do { _Pragma("unroll") for (int m = 0; m < 4; ++m) _Pragma("unroll") for (int k = 0; k < 2; ++k) dst[m][k] = *(const PG8_LAS bf16x8*)(lds + PG8_SA(b, h) + aoff + m * 2048 + k * 1024); } while (0)
; #define PG8_LDB(dst, b, h) do { _Pragma("unroll") for (int n = 0; n < 2; ++n) _Pragma("unroll") for (int k = 0; k < 2; ++k) dst[n][k] = *(const PG8_LAS bf16x8*)(lds + PG8_SB(b, h) + boff + n * 2048 + k * 1024); } while (0)
; #define PG8_MMA(ai, bj, At, Bt) do { __builtin_amdgcn_s_setprio(1); _Pragma("unroll") for (int m = 0; m < 4; ++m) _Pragma("unroll") for (int n = 0; n < 2; ++n) _Pragma("unroll") for (int k = 0; k < 2; ++k) \
;         acc[ai][bj][m][n] = mma16<Epi::F16>(Bt[n][k], At[m][k], acc[ai][bj][m][n]); __builtin_amdgcn_s_setprio(0); } while (0)
; #define PG8_WAIT_V(n) asm volatile("s_waitcnt vmcnt(" #n ")" ::: "memory")
; #define PG8_WAIT_L(n) asm volatile("s_waitcnt lgkmcnt(" #n ")" ::: "memory")
; #define PG8_BAR __builtin_amdgcn_s_barrier()
; #define PG8_SCHED __builtin_amdgcn_sched_barrier(0)
; template <class Epi, class Sched, bool ALIGN_EPI = false, bool SP2 = false>
; __device__ __forceinline__ void gemm_phase(PG8_LAS unsigned char* lds, const Gemm g, const Sched& S, const Epi& E, const int wave_in) {
;     ...
;             PG8_LDB(B0, 0, 0); PG8_LDB(B1, 0, 1); PG8_SCHED; PG8_LDA(At, 0, 0); PG8_STAGE(PG8_SA(1, 1), a1 + hstep, voffA);
;             PG8_WAIT_V(8); PG8_WAIT_L(0); PG8_BAR; PG8_MMA(0, 0, At, B0); PG8_MMA(0, 1, At, B1); PG8_BAR; PG8_SCHED;
;             PG8_LDA(At, 0, 1); PG8_STAGE(PG8_SB(0, 0), b2, voffB); PG8_STAGE(PG8_SB(0, 1), b2 + hstep, voffB); PG8_STAGE(PG8_SA(0, 0), a2, voffA);
;             PG8_WAIT_V(8); PG8_WAIT_L(0); PG8_BAR; PG8_MMA(1, 0, At, B0); PG8_MMA(1, 1, At, B1); PG8_BAR; PG8_SCHED;
.LBB0_418:
	v_add_u32_e32 v58, s28, v211
	v_add_u32_e32 v78, s72, v211
	ds_read_b128 v[42:45], v58
	ds_read_b128 v[46:49], v58 offset:1024
	ds_read_b128 v[54:57], v58 offset:2048
	ds_read_b128 v[58:61], v58 offset:3072
	ds_read_b128 v[66:69], v78
	ds_read_b128 v[70:73], v78 offset:1024
	ds_read_b128 v[74:77], v78 offset:2048
	ds_read_b128 v[78:81], v78 offset:3072
	s_add_u32 s86, s62, 0x100
	s_addc_u32 s87, s63, 0
	s_cmp_eq_u32 s13, 40
	s_cselect_b32 s91, s45, s87
	s_cselect_b32 s90, s44, s86
	s_cselect_b32 s37, s61, s12
	s_cselect_b32 s36, s60, s11
	v_lshl_add_u64 v[178:179], s[62:63], 0, v[220:221]
	s_add_i32 m0, s0, 0xc000
	ds_read_b128 v[98:101], v213
	ds_read_b128 v[102:105], v213 offset:1024
	ds_read_b128 v[106:109], v213 offset:2048
	ds_read_b128 v[118:121], v213 offset:3072
	ds_read_b128 v[130:133], v213 offset:4096
	ds_read_b128 v[138:141], v213 offset:5120
	ds_read_b128 v[146:149], v213 offset:6144
	ds_read_b128 v[158:161], v213 offset:7168
	global_load_lds_dwordx4 v[178:179], off
	v_lshl_add_u64 v[178:179], s[62:63], 0, v[222:223]
	s_add_i32 m0, s0, 0xe000
	s_nop 0
	global_load_lds_dwordx4 v[178:179], off
	s_waitcnt vmcnt(8)
	s_waitcnt lgkmcnt(0)
	s_barrier
	s_setprio 1
	s_waitcnt lgkmcnt(0)
	v_mfma_f32_16x16x32_bf16 v[190:193], v[54:57], v[98:101], v[190:193]
	v_mfma_f32_16x16x32_bf16 v[174:177], v[42:45], v[106:109], v[174:177]
	v_mfma_f32_16x16x32_bf16 v[170:173], v[54:57], v[106:109], v[170:173]
	v_mfma_f32_16x16x32_bf16 v[154:157], v[42:45], v[130:133], v[154:157]
	v_mfma_f32_16x16x32_bf16 v[150:153], v[54:57], v[130:133], v[150:153]
	v_mfma_f32_16x16x32_bf16 v[126:129], v[42:45], v[146:149], v[126:129]
	v_mfma_f32_16x16x32_bf16 v[122:125], v[54:57], v[146:149], v[122:125]
	v_mfma_f32_16x16x32_bf16 v[178:181], v[42:45], v[98:101], v[194:197]
	v_mfma_f32_16x16x32_bf16 v[190:193], v[58:61], v[102:105], v[190:193]
	v_mfma_f32_16x16x32_bf16 v[174:177], v[46:49], v[118:121], v[174:177]
	v_mfma_f32_16x16x32_bf16 v[170:173], v[58:61], v[118:121], v[170:173]
	v_mfma_f32_16x16x32_bf16 v[154:157], v[46:49], v[138:141], v[154:157]
	v_mfma_f32_16x16x32_bf16 v[150:153], v[58:61], v[138:141], v[150:153]
	v_mfma_f32_16x16x32_bf16 v[126:129], v[46:49], v[158:161], v[126:129]
	v_mfma_f32_16x16x32_bf16 v[122:125], v[58:61], v[158:161], v[122:125]
	v_mfma_f32_16x16x32_bf16 v[178:181], v[46:49], v[102:105], v[178:181]
	s_setprio 0
	s_setprio 1
	v_mfma_f32_16x16x32_bf16 v[186:189], v[66:69], v[98:101], v[186:189]
	v_mfma_f32_16x16x32_bf16 v[98:101], v[74:77], v[98:101], v[182:185]
	v_mfma_f32_16x16x32_bf16 v[186:189], v[70:73], v[102:105], v[186:189]
	v_mfma_f32_16x16x32_bf16 v[98:101], v[78:81], v[102:105], v[98:101]
	v_mfma_f32_16x16x32_bf16 v[102:105], v[66:69], v[106:109], v[166:169]
	v_mfma_f32_16x16x32_bf16 v[106:109], v[74:77], v[106:109], v[162:165]
	v_mfma_f32_16x16x32_bf16 v[114:117], v[66:69], v[146:149], v[114:117]
	v_mfma_f32_16x16x32_bf16 v[110:113], v[74:77], v[146:149], v[110:113]
	v_mfma_f32_16x16x32_bf16 v[102:105], v[70:73], v[118:121], v[102:105]
	v_mfma_f32_16x16x32_bf16 v[106:109], v[78:81], v[118:121], v[106:109]
	v_mfma_f32_16x16x32_bf16 v[118:121], v[66:69], v[130:133], v[142:145]
	v_mfma_f32_16x16x32_bf16 v[130:133], v[74:77], v[130:133], v[134:137]
	v_mfma_f32_16x16x32_bf16 v[114:117], v[70:73], v[158:161], v[114:117]
	v_mfma_f32_16x16x32_bf16 v[110:113], v[78:81], v[158:161], v[110:113]
	v_mfma_f32_16x16x32_bf16 v[118:121], v[70:73], v[138:141], v[118:121]
	v_mfma_f32_16x16x32_bf16 v[130:133], v[78:81], v[138:141], v[130:133]
	s_setprio 0
	s_barrier
	s_add_i32 s14, s28, s4
	v_lshl_add_u64 v[230:231], s[90:91], 0, v[214:215]
	v_lshl_add_u64 v[232:233], s[90:91], 0, v[216:217]
	s_mov_b32 m0, s0
	ds_read_b128 v[134:137], v213 offset:16384
	ds_read_b128 v[138:141], v213 offset:17408
	ds_read_b128 v[142:145], v213 offset:18432
	ds_read_b128 v[146:149], v213 offset:19456
	ds_read_b128 v[158:161], v213 offset:20480
	ds_read_b128 v[162:165], v213 offset:21504
	ds_read_b128 v[166:169], v213 offset:22528
	ds_read_b128 v[182:185], v213 offset:23552
	global_load_lds_dwordx4 v[230:231], off
	s_mov_b32 m0, s1
	v_lshl_add_u64 v[208:209], s[36:37], 0, v[0:1]
	global_load_lds_dwordx4 v[232:233], off
	s_mov_b32 m0, s14
	v_lshl_add_u64 v[228:229], s[36:37], 0, v[218:219]
	global_load_lds_dwordx4 v[208:209], off
	s_add_i32 m0, s14, 0x2000
	s_add_u32 s62, s36, 0xb0000
	s_addc_u32 s63, s37, 0
	s_add_i32 s14, s72, s4
	global_load_lds_dwordx4 v[228:229], off
	v_lshl_add_u64 v[194:195], s[62:63], 0, v[0:1]
	s_mov_b32 m0, s14
	s_nop 0
	global_load_lds_dwordx4 v[194:195], off
	v_lshl_add_u64 v[194:195], s[62:63], 0, v[218:219]
	s_add_i32 m0, s14, 0x2000
	s_nop 0
	global_load_lds_dwordx4 v[194:195], off
	s_waitcnt vmcnt(8)
	s_waitcnt lgkmcnt(0)
	s_barrier
; #define PG8_STAGE(bufoff, gbase, voff) do { _Pragma("unroll") for (int _i = 0; _i < 2; ++_i) \
;         __builtin_amdgcn_global_load_lds((const unsigned*)((const char*)(gbase) + (voff)[_i]), (PG8_LAS unsigned*)(lds + (bufoff) + ldsw + _i * 8192), 16, 0, 0); } while (0)
; #define PG8_LDA(dst, b, h) do { _Pragma("unroll") for (int m = 0; m < 4; ++m) _Pragma("unroll") for (int k = 0; k < 2; ++k) dst[m][k] = *(const PG8_LAS bf16x8*)(lds + PG8_SA(b, h) + aoff + m * 2048 + k * 1024); } while (0)
; #define PG8_LDB(dst, b, h) do { _Pragma("unroll") for (int n = 0; n < 2; ++n) _Pragma("unroll") for (int k = 0; k < 2; ++k) dst[n][k] = *(const PG8_LAS bf16x8*)(lds + PG8_SB(b, h) + boff + n * 2048 + k * 1024); } while (0)
; #define PG8_MMA(ai, bj, At, Bt) do { __builtin_amdgcn_s_setprio(1); _Pragma("unroll") for (int m = 0; m < 4; ++m) _Pragma("unroll") for (int n = 0; n < 2; ++n) _Pragma("unroll") for (int k = 0; k < 2; ++k) \
;         acc[ai][bj][m][n] = mma16<Epi::F16>(Bt[n][k], At[m][k], acc[ai][bj][m][n]); __builtin_amdgcn_s_setprio(0); } while (0)
; #define PG8_WAIT_V(n) asm volatile("s_waitcnt vmcnt(" #n ")" ::: "memory")
; #define PG8_WAIT_L(n) asm volatile("s_waitcnt lgkmcnt(" #n ")" ::: "memory")
; #define PG8_BAR __builtin_amdgcn_s_barrier()
; #define PG8_SCHED __builtin_amdgcn_sched_barrier(0)
; template <class Epi, class Sched, bool ALIGN_EPI = false, bool SP2 = false>
; __device__ __forceinline__ void gemm_phase(PG8_LAS unsigned char* lds, const Gemm g, const Sched& S, const Epi& E, const int wave_in) {
;     ...
;             PG8_WAIT_V(8); PG8_WAIT_L(0); PG8_BAR; PG8_MMA(1, 0, At, B0); PG8_MMA(1, 1, At, B1); PG8_BAR; PG8_SCHED;
;             PG8_LDB(B0, 1, 0); PG8_LDB(B1, 1, 1); PG8_SCHED; PG8_LDA(At, 1, 0); PG8_STAGE(PG8_SA(0, 1), a2 + hstep, voffA);
;             PG8_WAIT_V(8); PG8_WAIT_L(0); PG8_BAR; PG8_MMA(0, 0, At, B0); PG8_MMA(0, 1, At, B1); PG8_BAR; PG8_SCHED;
	s_setprio 1
	s_waitcnt lgkmcnt(0)
	v_mfma_f32_16x16x32_bf16 v[94:97], v[42:45], v[134:137], v[94:97]
	v_mfma_f32_16x16x32_bf16 v[90:93], v[54:57], v[134:137], v[90:93]
	v_mfma_f32_16x16x32_bf16 v[62:65], v[42:45], v[142:145], v[62:65]
	v_mfma_f32_16x16x32_bf16 v[50:53], v[54:57], v[142:145], v[50:53]
	v_mfma_f32_16x16x32_bf16 v[30:33], v[42:45], v[158:161], v[30:33]
	v_mfma_f32_16x16x32_bf16 v[26:29], v[54:57], v[158:161], v[26:29]
	v_mfma_f32_16x16x32_bf16 v[14:17], v[42:45], v[166:169], v[14:17]
	v_mfma_f32_16x16x32_bf16 v[10:13], v[54:57], v[166:169], v[10:13]
	v_mfma_f32_16x16x32_bf16 v[94:97], v[46:49], v[138:141], v[94:97]
	v_mfma_f32_16x16x32_bf16 v[90:93], v[58:61], v[138:141], v[90:93]
	v_mfma_f32_16x16x32_bf16 v[62:65], v[46:49], v[146:149], v[62:65]
	v_mfma_f32_16x16x32_bf16 v[50:53], v[58:61], v[146:149], v[50:53]
	v_mfma_f32_16x16x32_bf16 v[30:33], v[46:49], v[162:165], v[30:33]
	v_mfma_f32_16x16x32_bf16 v[26:29], v[58:61], v[162:165], v[26:29]
	v_mfma_f32_16x16x32_bf16 v[14:17], v[46:49], v[182:185], v[14:17]
	v_mfma_f32_16x16x32_bf16 v[10:13], v[58:61], v[182:185], v[10:13]
	s_setprio 0
	s_setprio 1
	v_mfma_f32_16x16x32_bf16 v[38:41], v[66:69], v[142:145], v[38:41]
	v_mfma_f32_16x16x32_bf16 v[34:37], v[74:77], v[142:145], v[34:37]
	v_mfma_f32_16x16x32_bf16 v[22:25], v[66:69], v[158:161], v[22:25]
	v_mfma_f32_16x16x32_bf16 v[18:21], v[74:77], v[158:161], v[18:21]
	v_mfma_f32_16x16x32_bf16 v[6:9], v[66:69], v[166:169], v[6:9]
	v_mfma_f32_16x16x32_bf16 v[2:5], v[74:77], v[166:169], v[2:5]
	v_mfma_f32_16x16x32_bf16 v[42:45], v[66:69], v[134:137], v[86:89]
	v_mfma_f32_16x16x32_bf16 v[46:49], v[74:77], v[134:137], v[82:85]
	v_mfma_f32_16x16x32_bf16 v[38:41], v[70:73], v[146:149], v[38:41]
	v_mfma_f32_16x16x32_bf16 v[34:37], v[78:81], v[146:149], v[34:37]
	v_mfma_f32_16x16x32_bf16 v[22:25], v[70:73], v[162:165], v[22:25]
	v_mfma_f32_16x16x32_bf16 v[18:21], v[78:81], v[162:165], v[18:21]
	v_mfma_f32_16x16x32_bf16 v[6:9], v[70:73], v[182:185], v[6:9]
	v_mfma_f32_16x16x32_bf16 v[2:5], v[78:81], v[182:185], v[2:5]
	v_mfma_f32_16x16x32_bf16 v[42:45], v[70:73], v[138:141], v[42:45]
	v_mfma_f32_16x16x32_bf16 v[46:49], v[78:81], v[138:141], v[46:49]
	s_setprio 0
	s_barrier
	v_add_u32_e32 v70, s73, v211
	v_add_u32_e32 v82, s74, v211
	ds_read_b128 v[54:57], v70
	ds_read_b128 v[58:61], v70 offset:1024
	ds_read_b128 v[66:69], v70 offset:2048
	ds_read_b128 v[70:73], v70 offset:3072
	ds_read_b128 v[74:77], v82
	ds_read_b128 v[78:81], v82 offset:1024
	ds_read_b128 v[138:141], v82 offset:2048
	ds_read_b128 v[146:149], v82 offset:3072
	s_add_u32 s62, s90, 0xb0000
	s_addc_u32 s63, s91, 0
	s_mov_b32 m0, s5
	v_lshl_add_u64 v[162:163], s[62:63], 0, v[214:215]
	ds_read_b128 v[82:85], v213 offset:32768
	ds_read_b128 v[86:89], v213 offset:33792
	ds_read_b128 v[134:137], v213 offset:34816
	ds_read_b128 v[142:145], v213 offset:35840
	ds_read_b128 v[158:161], v213 offset:36864
	ds_read_b128 v[198:201], v213 offset:37888
	ds_read_b128 v[202:205], v213 offset:38912
	ds_read_b128 v[224:227], v213 offset:39936
	global_load_lds_dwordx4 v[162:163], off
	v_lshl_add_u64 v[162:163], s[62:63], 0, v[216:217]
	s_mov_b32 m0, s82
	s_nop 0
	global_load_lds_dwordx4 v[162:163], off
	s_waitcnt vmcnt(8)
	s_waitcnt lgkmcnt(0)
	s_barrier
	s_setprio 1
	s_waitcnt lgkmcnt(0)
	v_mfma_f32_16x16x32_bf16 v[162:165], v[54:57], v[82:85], v[178:181]
	v_mfma_f32_16x16x32_bf16 v[194:197], v[58:61], v[86:89], v[162:165]
	v_mfma_f32_16x16x32_bf16 v[162:165], v[66:69], v[82:85], v[190:193]
	v_mfma_f32_16x16x32_bf16 v[190:193], v[70:73], v[86:89], v[162:165]
	v_mfma_f32_16x16x32_bf16 v[162:165], v[54:57], v[134:137], v[174:177]
	v_mfma_f32_16x16x32_bf16 v[174:177], v[58:61], v[142:145], v[162:165]
	v_mfma_f32_16x16x32_bf16 v[162:165], v[66:69], v[134:137], v[170:173]
	v_mfma_f32_16x16x32_bf16 v[154:157], v[54:57], v[158:161], v[154:157]
	v_mfma_f32_16x16x32_bf16 v[150:153], v[66:69], v[158:161], v[150:153]
	v_mfma_f32_16x16x32_bf16 v[126:129], v[54:57], v[202:205], v[126:129]
	v_mfma_f32_16x16x32_bf16 v[122:125], v[66:69], v[202:205], v[122:125]
	v_mfma_f32_16x16x32_bf16 v[170:173], v[70:73], v[142:145], v[162:165]
	v_mfma_f32_16x16x32_bf16 v[154:157], v[58:61], v[198:201], v[154:157]
	v_mfma_f32_16x16x32_bf16 v[150:153], v[70:73], v[198:201], v[150:153]
	v_mfma_f32_16x16x32_bf16 v[126:129], v[58:61], v[224:227], v[126:129]
	v_mfma_f32_16x16x32_bf16 v[122:125], v[70:73], v[224:227], v[122:125]
	s_setprio 0
	s_setprio 1
	v_mfma_f32_16x16x32_bf16 v[162:165], v[74:77], v[82:85], v[186:189]
	v_mfma_f32_16x16x32_bf16 v[82:85], v[138:141], v[82:85], v[98:101]
	v_mfma_f32_16x16x32_bf16 v[182:185], v[146:149], v[86:89], v[82:85]
	v_mfma_f32_16x16x32_bf16 v[82:85], v[74:77], v[134:137], v[102:105]
	v_mfma_f32_16x16x32_bf16 v[166:169], v[78:81], v[142:145], v[82:85]
	v_mfma_f32_16x16x32_bf16 v[82:85], v[138:141], v[134:137], v[106:109]
	v_mfma_f32_16x16x32_bf16 v[186:189], v[78:81], v[86:89], v[162:165]
	v_mfma_f32_16x16x32_bf16 v[162:165], v[146:149], v[142:145], v[82:85]
	v_mfma_f32_16x16x32_bf16 v[82:85], v[74:77], v[158:161], v[118:121]
	v_mfma_f32_16x16x32_bf16 v[142:145], v[78:81], v[198:201], v[82:85]
	v_mfma_f32_16x16x32_bf16 v[82:85], v[138:141], v[158:161], v[130:133]
	v_mfma_f32_16x16x32_bf16 v[134:137], v[146:149], v[198:201], v[82:85]
	v_mfma_f32_16x16x32_bf16 v[82:85], v[74:77], v[202:205], v[114:117]
	v_mfma_f32_16x16x32_bf16 v[114:117], v[78:81], v[224:227], v[82:85]
	v_mfma_f32_16x16x32_bf16 v[82:85], v[138:141], v[202:205], v[110:113]
	v_mfma_f32_16x16x32_bf16 v[110:113], v[146:149], v[224:227], v[82:85]
	s_setprio 0
	s_barrier
; #define PG8_STAGE(bufoff, gbase, voff) do { _Pragma("unroll") for (int _i = 0; _i < 2; ++_i) \
;         __builtin_amdgcn_global_load_lds((const unsigned*)((const char*)(gbase) + (voff)[_i]), (PG8_LAS unsigned*)(lds + (bufoff) + ldsw + _i * 8192), 16, 0, 0); } while (0)
; #define PG8_LDA(dst, b, h) do { _Pragma("unroll") for (int m = 0; m < 4; ++m) _Pragma("unroll") for (int k = 0; k < 2; ++k) dst[m][k] = *(const PG8_LAS bf16x8*)(lds + PG8_SA(b, h) + aoff + m * 2048 + k * 1024); } while (0)
; #define PG8_MMA(ai, bj, At, Bt) do { __builtin_amdgcn_s_setprio(1); _Pragma("unroll") for (int m = 0; m < 4; ++m) _Pragma("unroll") for (int n = 0; n < 2; ++n) _Pragma("unroll") for (int k = 0; k < 2; ++k) \
;         acc[ai][bj][m][n] = mma16<Epi::F16>(Bt[n][k], At[m][k], acc[ai][bj][m][n]); __builtin_amdgcn_s_setprio(0); } while (0)
; #define PG8_WAIT_V(n) asm volatile("s_waitcnt vmcnt(" #n ")" ::: "memory")
; #define PG8_WAIT_L(n) asm volatile("s_waitcnt lgkmcnt(" #n ")" ::: "memory")
; #define PG8_BAR __builtin_amdgcn_s_barrier()
; #define PG8_SCHED __builtin_amdgcn_sched_barrier(0)
; template <class Epi, class Sched, bool ALIGN_EPI = false, bool SP2 = false>
; __device__ __forceinline__ void gemm_phase(PG8_LAS unsigned char* lds, const Gemm g, const Sched& S, const Epi& E, const int wave_in) {
;     ...
;         for (int t = 0; t < nt; t += 2) {
;             const bool last = (t == nt - 2);
;             const char* a1 = cA + (size_t)(t + 1) * kstep;
;             const char* a2 = last ? nA : cA + (size_t)(t + 2) * kstep; const char* b2 = last ? nB : cB + (size_t)(t + 2) * kstep;
;             const char* a3 = a2 + kstep; const char* b3 = b2 + kstep;
;     ...
;             PG8_LDA(At, 1, 1); PG8_STAGE(PG8_SB(1, 0), b3, voffB); PG8_STAGE(PG8_SB(1, 1), b3 + hstep, voffB); PG8_STAGE(PG8_SA(1, 0), a3, voffA);
;             PG8_WAIT_V(8); PG8_WAIT_L(0); PG8_BAR; PG8_MMA(1, 0, At, B0); PG8_MMA(1, 1, At, B1); PG8_BAR; PG8_SCHED;
	s_add_i32 s14, s73, s4
	v_lshl_add_u64 v[86:87], v[230:231], 0, s[78:79]
	s_mov_b32 m0, s71
	s_nop 1
	ds_read_b128 v[82:85], v213 offset:49152
	ds_read_b128 v[98:101], v213 offset:50176
	ds_read_b128 v[102:105], v213 offset:51200
	ds_read_b128 v[106:109], v213 offset:52224
	ds_read_b128 v[118:121], v213 offset:53248
	ds_read_b128 v[130:133], v213 offset:54272
	ds_read_b128 v[158:161], v213 offset:55296
	ds_read_b128 v[178:181], v213 offset:56320
	global_load_lds_dwordx4 v[86:87], off
	v_lshl_add_u64 v[86:87], v[232:233], 0, s[78:79]
	s_mov_b32 m0, s6
	s_nop 0
	global_load_lds_dwordx4 v[86:87], off
	v_lshl_add_u64 v[86:87], v[208:209], 0, s[78:79]
	s_mov_b32 m0, s14
	s_nop 0
	global_load_lds_dwordx4 v[86:87], off
	s_add_i32 m0, s14, 0x2000
	s_add_u32 s36, s36, 0xb0080
	v_lshl_add_u64 v[86:87], v[228:229], 0, s[78:79]
	s_addc_u32 s37, s37, 0
	s_add_i32 s14, s74, s4
	global_load_lds_dwordx4 v[86:87], off
	v_lshl_add_u64 v[86:87], s[36:37], 0, v[0:1]
	s_mov_b32 m0, s14
	s_nop 0
	global_load_lds_dwordx4 v[86:87], off
	v_lshl_add_u64 v[86:87], s[36:37], 0, v[218:219]
	s_add_i32 m0, s14, 0x2000
	s_nop 0
	global_load_lds_dwordx4 v[86:87], off
	s_waitcnt vmcnt(8)
	s_waitcnt lgkmcnt(0)
	s_barrier
	s_setprio 1
	s_waitcnt lgkmcnt(0)
	v_mfma_f32_16x16x32_bf16 v[86:89], v[54:57], v[82:85], v[94:97]
	v_mfma_f32_16x16x32_bf16 v[94:97], v[58:61], v[98:101], v[86:89]
	v_mfma_f32_16x16x32_bf16 v[86:89], v[66:69], v[82:85], v[90:93]
	v_mfma_f32_16x16x32_bf16 v[62:65], v[54:57], v[102:105], v[62:65]
	v_mfma_f32_16x16x32_bf16 v[50:53], v[66:69], v[102:105], v[50:53]
	v_mfma_f32_16x16x32_bf16 v[30:33], v[54:57], v[118:121], v[30:33]
	v_mfma_f32_16x16x32_bf16 v[26:29], v[66:69], v[118:121], v[26:29]
	v_mfma_f32_16x16x32_bf16 v[14:17], v[54:57], v[158:161], v[14:17]
	v_mfma_f32_16x16x32_bf16 v[10:13], v[66:69], v[158:161], v[10:13]
	v_mfma_f32_16x16x32_bf16 v[90:93], v[70:73], v[98:101], v[86:89]
	v_mfma_f32_16x16x32_bf16 v[62:65], v[58:61], v[106:109], v[62:65]
	v_mfma_f32_16x16x32_bf16 v[50:53], v[70:73], v[106:109], v[50:53]
	v_mfma_f32_16x16x32_bf16 v[30:33], v[58:61], v[130:133], v[30:33]
	v_mfma_f32_16x16x32_bf16 v[26:29], v[70:73], v[130:133], v[26:29]
	v_mfma_f32_16x16x32_bf16 v[14:17], v[58:61], v[178:181], v[14:17]
	v_mfma_f32_16x16x32_bf16 v[10:13], v[70:73], v[178:181], v[10:13]
	s_setprio 0
	s_setprio 1
	v_mfma_f32_16x16x32_bf16 v[42:45], v[74:77], v[82:85], v[42:45]
	v_mfma_f32_16x16x32_bf16 v[86:89], v[78:81], v[98:101], v[42:45]
	v_mfma_f32_16x16x32_bf16 v[42:45], v[138:141], v[82:85], v[46:49]
	v_mfma_f32_16x16x32_bf16 v[38:41], v[74:77], v[102:105], v[38:41]
	v_mfma_f32_16x16x32_bf16 v[34:37], v[138:141], v[102:105], v[34:37]
	v_mfma_f32_16x16x32_bf16 v[22:25], v[74:77], v[118:121], v[22:25]
	v_mfma_f32_16x16x32_bf16 v[18:21], v[138:141], v[118:121], v[18:21]
	v_mfma_f32_16x16x32_bf16 v[6:9], v[74:77], v[158:161], v[6:9]
	v_mfma_f32_16x16x32_bf16 v[2:5], v[138:141], v[158:161], v[2:5]
	v_mfma_f32_16x16x32_bf16 v[82:85], v[146:149], v[98:101], v[42:45]
	v_mfma_f32_16x16x32_bf16 v[38:41], v[78:81], v[106:109], v[38:41]
	v_mfma_f32_16x16x32_bf16 v[34:37], v[146:149], v[106:109], v[34:37]
	v_mfma_f32_16x16x32_bf16 v[22:25], v[78:81], v[130:133], v[22:25]
	v_mfma_f32_16x16x32_bf16 v[18:21], v[146:149], v[130:133], v[18:21]
	v_mfma_f32_16x16x32_bf16 v[6:9], v[78:81], v[178:181], v[6:9]
	v_mfma_f32_16x16x32_bf16 v[2:5], v[146:149], v[178:181], v[2:5]
	s_setprio 0
	s_barrier
	s_add_i32 s13, s13, 2
	s_add_u32 s11, s11, 0x100
	s_addc_u32 s12, s12, 0
	s_cmp_gt_u32 s13, 41
	s_mov_b64 s[62:63], s[86:87]
	s_cbranch_scc0 .LBB0_418
	s_and_b64 vcc, exec, s[58:59]
	s_cbranch_vccz .LBB0_421
	s_barrier
